# P4 compress stage 2 epilogue: DPP/permlane-swap wave sum instead of six ds_bpermute round trips, k-norm gain loaded once per wave
# speedup vs baseline: 1.0073x; 1.0061x over previous
.LBB0_648:
	s_mul_hi_i32 s2, s26, 0x2ad5802b
	s_lshr_b32 s3, s2, 31
	s_ashr_i32 s2, s2, 10
	s_add_i32 s28, s2, s3
	v_lshl_or_b32 v16, s28, 6, v229
	v_ashrrev_i32_e32 v17, 31, v16
	v_lshl_add_u64 v[16:17], v[16:17], 2, v[2:3]
	global_load_dword v6, v[16:17], off
	s_mul_i32 s2, s28, 0x17e8
	s_sub_i32 s14, s26, s2
	s_ashr_i32 s29, s28, 31
	s_mul_i32 s2, s28, 0x1800
	s_ashr_i32 s15, s14, 31
	s_mul_hi_i32 s3, s28, 0x1800
	s_add_u32 s2, s2, s14
	s_addc_u32 s3, s3, s15
	s_lshl_b64 s[2:3], s[2:3], 9
	s_add_u32 s2, s16, s2
	s_addc_u32 s3, s21, s3
	s_lshl_b64 s[28:29], s[28:29], 16
	v_mov_b32_e32 v9, 0
	v_lshl_add_u64 v[16:17], v[0:1], 0, s[28:29]
	s_mov_b32 s15, -2
	v_mov_b32_e32 v18, 0
	v_mov_b32_e32 v19, v9
	s_add_i32 s80, s26, 5
	s_cmp_lt_i32 s80, s86
	s_cbranch_scc0 .Lc3_single
	s_sub_i32 s79, s26, s14
	s_mov_b64 s[60:61], s[2:3]
	s_mov_b64 s[82:83], 0x1000
	v_mov_b32_e32 v167, 0
	v_mov_b32_e32 v178, v16
	v_mov_b32_e32 v179, v17
	global_load_dword v215, v[12:13], off
	global_load_dwordx4 v[84:87], v167, s[60:61]
	global_load_dwordx4 v[88:91], v167, s[60:61] offset:512
	global_load_dwordx4 v[92:95], v167, s[60:61] offset:1024
	global_load_dwordx4 v[96:99], v167, s[60:61] offset:1536
	global_load_dwordx4 v[100:103], v167, s[60:61] offset:2048
	global_load_dwordx4 v[104:107], v167, s[60:61] offset:2560
	global_load_dword v231, v[178:179], off
	global_load_dword v232, v[178:179], off offset:256
	global_load_dword v233, v[178:179], off offset:512
	global_load_dword v234, v[178:179], off offset:768
	global_load_dword v235, v[178:179], off offset:1024
	global_load_dword v236, v[178:179], off offset:1280
	global_load_dword v237, v[178:179], off offset:1536
	global_load_dword v238, v[178:179], off offset:1792
	v_mov_b32_e32 v60, 0
	v_mov_b32_e32 v61, 0
	v_mov_b32_e32 v62, 0
	v_mov_b32_e32 v64, 0
	v_mov_b32_e32 v65, 0
	v_mov_b32_e32 v66, 0
	v_mov_b32_e32 v68, 0
	v_mov_b32_e32 v69, 0
	v_mov_b32_e32 v70, 0
	v_mov_b32_e32 v72, 0
	v_mov_b32_e32 v73, 0
	v_mov_b32_e32 v74, 0
	v_mov_b32_e32 v76, 0
	v_mov_b32_e32 v77, 0
	v_mov_b32_e32 v78, 0
	v_mov_b32_e32 v80, 0
	v_mov_b32_e32 v81, 0
	v_mov_b32_e32 v82, 0
	s_mov_b32 s77, 0
	s_waitcnt vmcnt(14)
	v_mov_b32_e32 v59, v6
	v_mov_b32_e32 v63, v6
	v_mov_b32_e32 v67, v6
	v_mov_b32_e32 v71, v6
	v_mov_b32_e32 v75, v6
	v_mov_b32_e32 v79, v6

.LBB0_654:
	s_andn2_b64 vcc, exec, s[2:3]
	s_cbranch_vccnz .LBB0_647
	v_mov_b32_e32 v6, v215
	v_mul_f32_e32 v9, v11, v11
	v_xor_b32_e32 v17, 32, v22
	v_cmp_lt_i32_e32 vcc, v17, v26
	v_add_f32_dpp v9, v9, v9 quad_perm:[1,0,3,2] row_mask:0xf bank_mask:0xf
	s_nop 1
	v_add_f32_dpp v9, v9, v9 quad_perm:[2,3,0,1] row_mask:0xf bank_mask:0xf
	v_cndmask_b32_e32 v17, v22, v17, vcc
	s_nop 0
	v_add_f32_dpp v9, v9, v9 row_half_mirror row_mask:0xf bank_mask:0xf
	v_lshlrev_b32_e32 v17, 2, v17
	s_nop 0
	v_add_f32_dpp v9, v9, v9 row_mirror row_mask:0xf bank_mask:0xf
	s_nop 0
	v_mov_b32_e32 v16, v9
	s_nop 1
	v_permlane16_swap_b32 v9, v16
	s_nop 0
	v_add_f32_e32 v9, v9, v16
	v_mov_b32_e32 v16, v9
	s_nop 1
	v_permlane32_swap_b32 v9, v16
	s_nop 0
	v_add_f32_e32 v9, v9, v16
	v_fmamk_f32 v9, v9, 0x3c800000, v20
	v_mul_f32_e32 v16, 0x4f800000, v9
	v_cmp_gt_f32_e32 vcc, s20, v9
	s_nop 1
	v_cndmask_b32_e32 v9, v9, v16, vcc
	v_sqrt_f32_e32 v16, v9
	s_nop 0
	v_add_u32_e32 v18, -1, v16
	v_add_u32_e32 v19, 1, v16
	v_fma_f32 v27, -v18, v16, v9
	v_fma_f32 v28, -v19, v16, v9
	v_cmp_ge_f32_e64 s[2:3], 0, v27
	s_nop 1
	v_cndmask_b32_e64 v16, v16, v18, s[2:3]
	v_cmp_lt_f32_e64 s[2:3], 0, v28
	s_nop 1
	v_cndmask_b32_e64 v16, v16, v19, s[2:3]
	v_mul_f32_e32 v18, 0x37800000, v16
	v_cndmask_b32_e32 v16, v16, v18, vcc
	v_cmp_class_f32_e32 vcc, v9, v21
	s_nop 1
	v_cndmask_b32_e32 v9, v16, v9, vcc
	v_div_scale_f32 v16, s[2:3], v9, v9, 1.0
	v_rcp_f32_e32 v18, v16
	v_div_scale_f32 v19, vcc, 1.0, v9, 1.0
	s_lshl_b32 s2, s27, 4
	v_fma_f32 v27, -v16, v18, 1.0
	v_fmac_f32_e32 v18, v27, v18
	v_mul_f32_e32 v27, v19, v18
	v_fma_f32 v28, -v16, v27, v19
	v_fmac_f32_e32 v27, v28, v18
	v_fma_f32 v16, -v16, v27, v19
	v_div_fmas_f32 v16, v16, v18, v27
	v_div_fixup_f32 v9, v16, v9, 1.0
	v_mul_f32_e32 v9, v11, v9
	s_waitcnt vmcnt(0)
	v_mul_f32_e32 v16, v6, v9
	ds_bpermute_b32 v17, v17, v16
	s_ashr_i32 s3, s2, 31
	s_lshl_b64 s[2:3], s[2:3], 8
	v_lshl_add_u64 v[18:19], v[14:15], 0, s[2:3]
	v_lshl_add_u64 v[18:19], v[18:19], 0, s[8:9]
	s_and_saveexec_b64 s[2:3], s[0:1]
	s_xor_b64 s[2:3], exec, s[2:3]
	s_cbranch_execz .LBB0_657
	flat_load_dwordx2 v[18:19], v[18:19]
	s_waitcnt vmcnt(0) lgkmcnt(0)
	v_pk_mul_f32 v[16:17], v[18:19], v[16:17]
	s_nop 0
	v_add_f32_e32 v6, v17, v16
